# compress_item partial-bias gather: 16 loads issued together and summed in the same order (was load, wait, add 16 times)
# baseline (speedup 1.0000x reference)
; #define MFMA16(a, b, c) __builtin_amdgcn_mfma_f32_16x16x32_bf16((a), (b), (c), 0, 0, 0)
; DI void compress_item(const Args& a, int l, int item, LAS unsigned char* lds) {
;     ...
;     const bf16_t* w1 = W + W_C1 + (size_t)kv * 262144 + (size_t)(wid * 16 + fr) * 2048 + fq * 8;
;     int tk0[2];
; #pragma unroll
;     for (int m = 0; m < 2; ++m) tk0[m] = 16 * (nq * 32 + m * 16 + fr);
; #pragma unroll 1
;     for (int k8 = 0; k8 < 64; k8 += 8) {
;         bf16x8 bfr[8], af[8][2];
; #pragma unroll
;         for (int kk = 0; kk < 8; ++kk) {
;             const int ks = k8 + kk, tokoff = ks >> 1, dcol = (ks & 1) * 32 + fq * 8;
;             bfr[kk] = *(const bf16x8*)(w1 + ks * 32);
; #pragma unroll
;             for (int m = 0; m < 2; ++m) { int tk = tk0[m] + tokoff; tk = tk > SEQ - 1 ? SEQ - 1 : tk; af[kk][m] = *(const bf16x8*)(PROJ + ((size_t)b * SEQ + tk) * PP + colbase + dcol); }
;         }
; #pragma unroll
;         for (int kk = 0; kk < 8; ++kk)
; #pragma unroll
;             for (int m = 0; m < 2; ++m) acc[m] = MFMA16(af[kk][m], bfr[kk], acc[m]);
;     }
.LBB0_604:
	v_lshl_add_u64 v[208:209], v[18:19], 0, v[12:13]
	s_and_b32 s14, s10, 7
	s_lshl_b32 s14, s14, 9
	v_bfe_u32 v181, v9, 5, 4
	v_bfe_u32 v182, v9, 3, 2
	v_and_b32_e32 v183, 7, v9
	v_lshl_add_u32 v178, v181, 4, v182
	v_add_u32_e32 v178, s14, v178
	v_lshlrev_b32_e32 v176, 4, v183
	v_sub_u32_e32 v176, v176, v12
	v_ashrrev_i32_e32 v177, 31, v176
	v_lshl_add_u64 v[252:253], v[14:15], 0, v[176:177]
	v_mul_u32_u24_e32 v179, 544, v181
	v_lshl_add_u32 v179, v182, 7, v179
	v_lshl_add_u32 v179, v183, 4, v179
	v_add_u32_e32 v179, 0x10000, v179
	v_mul_u32_u24_e32 v180, 544, v21
	v_lshl_add_u32 v180, v20, 4, v180
	v_add_u32_e32 v180, 0x10000, v180
	v_add_u32_e32 v251, 0, v178
	v_min_u32_e32 v251, 0xfff, v251
	v_or_b32_e32 v251, s6, v251
	v_mul_u32_u24_e32 v128, 0x1830, v251
	v_lshl_add_u64 v[254:255], v[252:253], 0, v[128:129]
	global_load_dwordx4 v[168:171], v[254:255], off
	v_add_u32_e32 v251, 0x100, v178
	v_min_u32_e32 v251, 0xfff, v251
	v_or_b32_e32 v251, s6, v251
	v_mul_u32_u24_e32 v128, 0x1830, v251
	v_lshl_add_u64 v[254:255], v[252:253], 0, v[128:129]
	global_load_dwordx4 v[172:175], v[254:255], off
	global_load_dwordx4 v[24:27], v[208:209], off offset:-256
	global_load_dwordx4 v[28:31], v[208:209], off offset:-192
	global_load_dwordx4 v[32:35], v[208:209], off offset:-128
	global_load_dwordx4 v[36:39], v[208:209], off offset:-64
	global_load_dwordx4 v[40:43], v[208:209], off
	global_load_dwordx4 v[44:47], v[208:209], off offset:64
	global_load_dwordx4 v[48:51], v[208:209], off offset:128
	global_load_dwordx4 v[52:55], v[208:209], off offset:192
	global_load_dwordx4 v[56:59], v[208:209], off offset:256
	global_load_dwordx4 v[60:63], v[208:209], off offset:320
	global_load_dwordx4 v[64:67], v[208:209], off offset:384
	global_load_dwordx4 v[68:71], v[208:209], off offset:448
	global_load_dwordx4 v[72:75], v[208:209], off offset:512
	global_load_dwordx4 v[76:79], v[208:209], off offset:576
	global_load_dwordx4 v[80:83], v[208:209], off offset:640
	global_load_dwordx4 v[84:87], v[208:209], off offset:704
	s_waitcnt vmcnt(16)
	ds_write_b128 v179, v[168:171] offset:0
	ds_write_b128 v179, v[172:175] offset:8704
	v_add_u32_e32 v251, 4, v178
	v_min_u32_e32 v251, 0xfff, v251
	v_or_b32_e32 v251, s6, v251
	v_mul_u32_u24_e32 v128, 0x1830, v251
	v_lshl_add_u64 v[254:255], v[252:253], 0, v[128:129]
	global_load_dwordx4 v[168:171], v[254:255], off
	v_add_u32_e32 v251, 0x104, v178
	v_min_u32_e32 v251, 0xfff, v251
	v_or_b32_e32 v251, s6, v251
	v_mul_u32_u24_e32 v128, 0x1830, v251
	v_lshl_add_u64 v[254:255], v[252:253], 0, v[128:129]
	global_load_dwordx4 v[172:175], v[254:255], off
	s_waitcnt lgkmcnt(0)
	s_barrier
	ds_read_b128 v[88:91], v180 offset:0
	ds_read_b128 v[92:95], v180 offset:8704
	ds_read_b128 v[96:99], v180 offset:64
	ds_read_b128 v[100:103], v180 offset:8768
	ds_read_b128 v[104:107], v180 offset:128
	ds_read_b128 v[108:111], v180 offset:8832
	ds_read_b128 v[112:115], v180 offset:192
	ds_read_b128 v[116:119], v180 offset:8896
	ds_read_b128 v[120:123], v180 offset:256
	ds_read_b128 v[124:127], v180 offset:8960
	ds_read_b128 v[130:133], v180 offset:320
	ds_read_b128 v[134:137], v180 offset:9024
	ds_read_b128 v[138:141], v180 offset:384
	ds_read_b128 v[142:145], v180 offset:9088
	ds_read_b128 v[146:149], v180 offset:448
	ds_read_b128 v[150:153], v180 offset:9152
	s_waitcnt vmcnt(17)
	s_waitcnt lgkmcnt(15)
	v_mfma_f32_16x16x32_bf16 v[4:7], v[88:91], v[24:27], v[4:7]
	s_waitcnt lgkmcnt(14)
	v_mfma_f32_16x16x32_bf16 v[0:3], v[92:95], v[24:27], v[0:3]
	s_waitcnt vmcnt(16)
	s_waitcnt lgkmcnt(13)
	v_mfma_f32_16x16x32_bf16 v[4:7], v[96:99], v[28:31], v[4:7]
	s_waitcnt lgkmcnt(12)
	v_mfma_f32_16x16x32_bf16 v[0:3], v[100:103], v[28:31], v[0:3]
	s_waitcnt vmcnt(15)
	s_waitcnt lgkmcnt(11)
	v_mfma_f32_16x16x32_bf16 v[4:7], v[104:107], v[32:35], v[4:7]
	s_waitcnt lgkmcnt(10)
	v_mfma_f32_16x16x32_bf16 v[0:3], v[108:111], v[32:35], v[0:3]
	s_waitcnt vmcnt(14)
	s_waitcnt lgkmcnt(9)
	v_mfma_f32_16x16x32_bf16 v[4:7], v[112:115], v[36:39], v[4:7]
	s_waitcnt lgkmcnt(8)
	v_mfma_f32_16x16x32_bf16 v[0:3], v[116:119], v[36:39], v[0:3]
	s_waitcnt vmcnt(13)
	s_waitcnt lgkmcnt(7)
	v_mfma_f32_16x16x32_bf16 v[4:7], v[120:123], v[40:43], v[4:7]
	s_waitcnt lgkmcnt(6)
	v_mfma_f32_16x16x32_bf16 v[0:3], v[124:127], v[40:43], v[0:3]
	s_waitcnt vmcnt(12)
	s_waitcnt lgkmcnt(5)
	v_mfma_f32_16x16x32_bf16 v[4:7], v[130:133], v[44:47], v[4:7]
	s_waitcnt lgkmcnt(4)
	v_mfma_f32_16x16x32_bf16 v[0:3], v[134:137], v[44:47], v[0:3]
	s_waitcnt vmcnt(11)
	s_waitcnt lgkmcnt(3)
	v_mfma_f32_16x16x32_bf16 v[4:7], v[138:141], v[48:51], v[4:7]
	s_waitcnt lgkmcnt(2)
	v_mfma_f32_16x16x32_bf16 v[0:3], v[142:145], v[48:51], v[0:3]
	s_waitcnt vmcnt(10)
	s_waitcnt lgkmcnt(1)
	v_mfma_f32_16x16x32_bf16 v[4:7], v[146:149], v[52:55], v[4:7]
	s_waitcnt lgkmcnt(0)
	v_mfma_f32_16x16x32_bf16 v[0:3], v[150:153], v[52:55], v[0:3]
	global_load_dwordx4 v[24:27], v[208:209], off offset:768
	global_load_dwordx4 v[28:31], v[208:209], off offset:832
	global_load_dwordx4 v[32:35], v[208:209], off offset:896
	global_load_dwordx4 v[36:39], v[208:209], off offset:960
	global_load_dwordx4 v[40:43], v[208:209], off offset:1024
	global_load_dwordx4 v[44:47], v[208:209], off offset:1088
	global_load_dwordx4 v[48:51], v[208:209], off offset:1152
	global_load_dwordx4 v[52:55], v[208:209], off offset:1216
	s_waitcnt vmcnt(8)
	ds_write_b128 v179, v[168:171] offset:17408
	ds_write_b128 v179, v[172:175] offset:26112
	v_add_u32_e32 v251, 8, v178
	v_min_u32_e32 v251, 0xfff, v251
	v_or_b32_e32 v251, s6, v251
	v_mul_u32_u24_e32 v128, 0x1830, v251
	v_lshl_add_u64 v[254:255], v[252:253], 0, v[128:129]
	global_load_dwordx4 v[168:171], v[254:255], off
	v_add_u32_e32 v251, 0x108, v178
	v_min_u32_e32 v251, 0xfff, v251
	v_or_b32_e32 v251, s6, v251
	v_mul_u32_u24_e32 v128, 0x1830, v251
	v_lshl_add_u64 v[254:255], v[252:253], 0, v[128:129]
	global_load_dwordx4 v[172:175], v[254:255], off
	s_waitcnt lgkmcnt(0)
	s_barrier
; #define MFMA16(a, b, c) __builtin_amdgcn_mfma_f32_16x16x32_bf16((a), (b), (c), 0, 0, 0)
; DI void compress_item(const Args& a, int l, int item, LAS unsigned char* lds) {
;     ...
; #pragma unroll 1
;     for (int k8 = 0; k8 < 64; k8 += 8) {
;         bf16x8 bfr[8], af[8][2];
; #pragma unroll
;         for (int kk = 0; kk < 8; ++kk) {
;             const int ks = k8 + kk, tokoff = ks >> 1, dcol = (ks & 1) * 32 + fq * 8;
;             bfr[kk] = *(const bf16x8*)(w1 + ks * 32);
; #pragma unroll
;             for (int m = 0; m < 2; ++m) { int tk = tk0[m] + tokoff; tk = tk > SEQ - 1 ? SEQ - 1 : tk; af[kk][m] = *(const bf16x8*)(PROJ + ((size_t)b * SEQ + tk) * PP + colbase + dcol); }
;         }
; #pragma unroll
;         for (int kk = 0; kk < 8; ++kk)
; #pragma unroll
;             for (int m = 0; m < 2; ++m) acc[m] = MFMA16(af[kk][m], bfr[kk], acc[m]);
;     }
	ds_read_b128 v[88:91], v180 offset:17408
	ds_read_b128 v[92:95], v180 offset:26112
	ds_read_b128 v[96:99], v180 offset:17472
	ds_read_b128 v[100:103], v180 offset:26176
	ds_read_b128 v[104:107], v180 offset:17536
	ds_read_b128 v[108:111], v180 offset:26240
	ds_read_b128 v[112:115], v180 offset:17600
	ds_read_b128 v[116:119], v180 offset:26304
	ds_read_b128 v[120:123], v180 offset:17664
	ds_read_b128 v[124:127], v180 offset:26368
	ds_read_b128 v[130:133], v180 offset:17728
	ds_read_b128 v[134:137], v180 offset:26432
	ds_read_b128 v[138:141], v180 offset:17792
	ds_read_b128 v[142:145], v180 offset:26496
	ds_read_b128 v[146:149], v180 offset:17856
	ds_read_b128 v[150:153], v180 offset:26560
	s_waitcnt vmcnt(19)
	s_waitcnt lgkmcnt(15)
	v_mfma_f32_16x16x32_bf16 v[4:7], v[88:91], v[56:59], v[4:7]
	s_waitcnt lgkmcnt(14)
	v_mfma_f32_16x16x32_bf16 v[0:3], v[92:95], v[56:59], v[0:3]
	s_waitcnt vmcnt(18)
	s_waitcnt lgkmcnt(13)
	v_mfma_f32_16x16x32_bf16 v[4:7], v[96:99], v[60:63], v[4:7]
	s_waitcnt lgkmcnt(12)
	v_mfma_f32_16x16x32_bf16 v[0:3], v[100:103], v[60:63], v[0:3]
	s_waitcnt vmcnt(17)
	s_waitcnt lgkmcnt(11)
	v_mfma_f32_16x16x32_bf16 v[4:7], v[104:107], v[64:67], v[4:7]
	s_waitcnt lgkmcnt(10)
	v_mfma_f32_16x16x32_bf16 v[0:3], v[108:111], v[64:67], v[0:3]
	s_waitcnt vmcnt(16)
	s_waitcnt lgkmcnt(9)
	v_mfma_f32_16x16x32_bf16 v[4:7], v[112:115], v[68:71], v[4:7]
	s_waitcnt lgkmcnt(8)
	v_mfma_f32_16x16x32_bf16 v[0:3], v[116:119], v[68:71], v[0:3]
	s_waitcnt vmcnt(15)
	s_waitcnt lgkmcnt(7)
	v_mfma_f32_16x16x32_bf16 v[4:7], v[120:123], v[72:75], v[4:7]
	s_waitcnt lgkmcnt(6)
	v_mfma_f32_16x16x32_bf16 v[0:3], v[124:127], v[72:75], v[0:3]
	s_waitcnt vmcnt(14)
	s_waitcnt lgkmcnt(5)
	v_mfma_f32_16x16x32_bf16 v[4:7], v[130:133], v[76:79], v[4:7]
	s_waitcnt lgkmcnt(4)
	v_mfma_f32_16x16x32_bf16 v[0:3], v[134:137], v[76:79], v[0:3]
	s_waitcnt vmcnt(13)
	s_waitcnt lgkmcnt(3)
	v_mfma_f32_16x16x32_bf16 v[4:7], v[138:141], v[80:83], v[4:7]
	s_waitcnt lgkmcnt(2)
	v_mfma_f32_16x16x32_bf16 v[0:3], v[142:145], v[80:83], v[0:3]
	s_waitcnt vmcnt(12)
	s_waitcnt lgkmcnt(1)
	v_mfma_f32_16x16x32_bf16 v[4:7], v[146:149], v[84:87], v[4:7]
	s_waitcnt lgkmcnt(0)
	v_mfma_f32_16x16x32_bf16 v[0:3], v[150:153], v[84:87], v[0:3]
	global_load_dwordx4 v[56:59], v[208:209], off offset:1280
	global_load_dwordx4 v[60:63], v[208:209], off offset:1344
	global_load_dwordx4 v[64:67], v[208:209], off offset:1408
	global_load_dwordx4 v[68:71], v[208:209], off offset:1472
	global_load_dwordx4 v[72:75], v[208:209], off offset:1536
	global_load_dwordx4 v[76:79], v[208:209], off offset:1600
	global_load_dwordx4 v[80:83], v[208:209], off offset:1664
	global_load_dwordx4 v[84:87], v[208:209], off offset:1728
	s_waitcnt vmcnt(8)
	ds_write_b128 v179, v[168:171] offset:0
	ds_write_b128 v179, v[172:175] offset:8704
	v_add_u32_e32 v251, 12, v178
	v_min_u32_e32 v251, 0xfff, v251
	v_or_b32_e32 v251, s6, v251
	v_mul_u32_u24_e32 v128, 0x1830, v251
	v_lshl_add_u64 v[254:255], v[252:253], 0, v[128:129]
	global_load_dwordx4 v[168:171], v[254:255], off
	v_add_u32_e32 v251, 0x10c, v178
	v_min_u32_e32 v251, 0xfff, v251
	v_or_b32_e32 v251, s6, v251
	v_mul_u32_u24_e32 v128, 0x1830, v251
	v_lshl_add_u64 v[254:255], v[252:253], 0, v[128:129]
	global_load_dwordx4 v[172:175], v[254:255], off
	s_waitcnt lgkmcnt(0)
	s_barrier
	ds_read_b128 v[88:91], v180 offset:0
	ds_read_b128 v[92:95], v180 offset:8704
	ds_read_b128 v[96:99], v180 offset:64
	ds_read_b128 v[100:103], v180 offset:8768
	ds_read_b128 v[104:107], v180 offset:128
	ds_read_b128 v[108:111], v180 offset:8832
	ds_read_b128 v[112:115], v180 offset:192
	ds_read_b128 v[116:119], v180 offset:8896
	ds_read_b128 v[120:123], v180 offset:256
	ds_read_b128 v[124:127], v180 offset:8960
	ds_read_b128 v[130:133], v180 offset:320
	ds_read_b128 v[134:137], v180 offset:9024
	ds_read_b128 v[138:141], v180 offset:384
	ds_read_b128 v[142:145], v180 offset:9088
	ds_read_b128 v[146:149], v180 offset:448
	ds_read_b128 v[150:153], v180 offset:9152
	s_waitcnt vmcnt(19)
	s_waitcnt lgkmcnt(15)
	v_mfma_f32_16x16x32_bf16 v[4:7], v[88:91], v[24:27], v[4:7]
	s_waitcnt lgkmcnt(14)
	v_mfma_f32_16x16x32_bf16 v[0:3], v[92:95], v[24:27], v[0:3]
	s_waitcnt vmcnt(18)
	s_waitcnt lgkmcnt(13)
	v_mfma_f32_16x16x32_bf16 v[4:7], v[96:99], v[28:31], v[4:7]
	s_waitcnt lgkmcnt(12)
	v_mfma_f32_16x16x32_bf16 v[0:3], v[100:103], v[28:31], v[0:3]
	s_waitcnt vmcnt(17)
	s_waitcnt lgkmcnt(11)
	v_mfma_f32_16x16x32_bf16 v[4:7], v[104:107], v[32:35], v[4:7]
	s_waitcnt lgkmcnt(10)
	v_mfma_f32_16x16x32_bf16 v[0:3], v[108:111], v[32:35], v[0:3]
	s_waitcnt vmcnt(16)
	s_waitcnt lgkmcnt(9)
	v_mfma_f32_16x16x32_bf16 v[4:7], v[112:115], v[36:39], v[4:7]
	s_waitcnt lgkmcnt(8)
	v_mfma_f32_16x16x32_bf16 v[0:3], v[116:119], v[36:39], v[0:3]
	s_waitcnt vmcnt(15)
	s_waitcnt lgkmcnt(7)
	v_mfma_f32_16x16x32_bf16 v[4:7], v[120:123], v[40:43], v[4:7]
	s_waitcnt lgkmcnt(6)
	v_mfma_f32_16x16x32_bf16 v[0:3], v[124:127], v[40:43], v[0:3]
	s_waitcnt vmcnt(14)
	s_waitcnt lgkmcnt(5)
	v_mfma_f32_16x16x32_bf16 v[4:7], v[130:133], v[44:47], v[4:7]
	s_waitcnt lgkmcnt(4)
	v_mfma_f32_16x16x32_bf16 v[0:3], v[134:137], v[44:47], v[0:3]
	s_waitcnt vmcnt(13)
	s_waitcnt lgkmcnt(3)
	v_mfma_f32_16x16x32_bf16 v[4:7], v[138:141], v[48:51], v[4:7]
	s_waitcnt lgkmcnt(2)
	v_mfma_f32_16x16x32_bf16 v[0:3], v[142:145], v[48:51], v[0:3]
	s_waitcnt vmcnt(12)
	s_waitcnt lgkmcnt(1)
	v_mfma_f32_16x16x32_bf16 v[4:7], v[146:149], v[52:55], v[4:7]
	s_waitcnt lgkmcnt(0)
	v_mfma_f32_16x16x32_bf16 v[0:3], v[150:153], v[52:55], v[0:3]
	global_load_dwordx4 v[24:27], v[208:209], off offset:1792
	global_load_dwordx4 v[28:31], v[208:209], off offset:1856
	global_load_dwordx4 v[32:35], v[208:209], off offset:1920
	global_load_dwordx4 v[36:39], v[208:209], off offset:1984
	global_load_dwordx4 v[40:43], v[208:209], off offset:2048
	global_load_dwordx4 v[44:47], v[208:209], off offset:2112
	global_load_dwordx4 v[48:51], v[208:209], off offset:2176
	global_load_dwordx4 v[52:55], v[208:209], off offset:2240
	s_waitcnt vmcnt(8)
	ds_write_b128 v179, v[168:171] offset:17408
	ds_write_b128 v179, v[172:175] offset:26112
	v_add_u32_e32 v251, 16, v178
	v_min_u32_e32 v251, 0xfff, v251
	v_or_b32_e32 v251, s6, v251
	v_mul_u32_u24_e32 v128, 0x1830, v251
	v_lshl_add_u64 v[254:255], v[252:253], 0, v[128:129]
	global_load_dwordx4 v[168:171], v[254:255], off
	v_add_u32_e32 v251, 0x110, v178
	v_min_u32_e32 v251, 0xfff, v251
	v_or_b32_e32 v251, s6, v251
	v_mul_u32_u24_e32 v128, 0x1830, v251
	v_lshl_add_u64 v[254:255], v[252:253], 0, v[128:129]
	global_load_dwordx4 v[172:175], v[254:255], off
	s_waitcnt lgkmcnt(0)
	s_barrier
; #define MFMA16(a, b, c) __builtin_amdgcn_mfma_f32_16x16x32_bf16((a), (b), (c), 0, 0, 0)
; DI void compress_item(const Args& a, int l, int item, LAS unsigned char* lds) {
;     ...
; #pragma unroll 1
;     for (int k8 = 0; k8 < 64; k8 += 8) {
;         bf16x8 bfr[8], af[8][2];
; #pragma unroll
;         for (int kk = 0; kk < 8; ++kk) {
;             const int ks = k8 + kk, tokoff = ks >> 1, dcol = (ks & 1) * 32 + fq * 8;
;             bfr[kk] = *(const bf16x8*)(w1 + ks * 32);
; #pragma unroll
;             for (int m = 0; m < 2; ++m) { int tk = tk0[m] + tokoff; tk = tk > SEQ - 1 ? SEQ - 1 : tk; af[kk][m] = *(const bf16x8*)(PROJ + ((size_t)b * SEQ + tk) * PP + colbase + dcol); }
;         }
; #pragma unroll
;         for (int kk = 0; kk < 8; ++kk)
; #pragma unroll
;             for (int m = 0; m < 2; ++m) acc[m] = MFMA16(af[kk][m], bfr[kk], acc[m]);
;     }
	ds_read_b128 v[88:91], v180 offset:17408
	ds_read_b128 v[92:95], v180 offset:26112
	ds_read_b128 v[96:99], v180 offset:17472
	ds_read_b128 v[100:103], v180 offset:26176
	ds_read_b128 v[104:107], v180 offset:17536
	ds_read_b128 v[108:111], v180 offset:26240
	ds_read_b128 v[112:115], v180 offset:17600
	ds_read_b128 v[116:119], v180 offset:26304
	ds_read_b128 v[120:123], v180 offset:17664
	ds_read_b128 v[124:127], v180 offset:26368
	ds_read_b128 v[130:133], v180 offset:17728
	ds_read_b128 v[134:137], v180 offset:26432
	ds_read_b128 v[138:141], v180 offset:17792
	ds_read_b128 v[142:145], v180 offset:26496
	ds_read_b128 v[146:149], v180 offset:17856
	ds_read_b128 v[150:153], v180 offset:26560
	s_waitcnt vmcnt(19)
	s_waitcnt lgkmcnt(15)
	v_mfma_f32_16x16x32_bf16 v[4:7], v[88:91], v[56:59], v[4:7]
	s_waitcnt lgkmcnt(14)
	v_mfma_f32_16x16x32_bf16 v[0:3], v[92:95], v[56:59], v[0:3]
	s_waitcnt vmcnt(18)
	s_waitcnt lgkmcnt(13)
	v_mfma_f32_16x16x32_bf16 v[4:7], v[96:99], v[60:63], v[4:7]
	s_waitcnt lgkmcnt(12)
	v_mfma_f32_16x16x32_bf16 v[0:3], v[100:103], v[60:63], v[0:3]
	s_waitcnt vmcnt(17)
	s_waitcnt lgkmcnt(11)
	v_mfma_f32_16x16x32_bf16 v[4:7], v[104:107], v[64:67], v[4:7]
	s_waitcnt lgkmcnt(10)
	v_mfma_f32_16x16x32_bf16 v[0:3], v[108:111], v[64:67], v[0:3]
	s_waitcnt vmcnt(16)
	s_waitcnt lgkmcnt(9)
	v_mfma_f32_16x16x32_bf16 v[4:7], v[112:115], v[68:71], v[4:7]
	s_waitcnt lgkmcnt(8)
	v_mfma_f32_16x16x32_bf16 v[0:3], v[116:119], v[68:71], v[0:3]
	s_waitcnt vmcnt(15)
	s_waitcnt lgkmcnt(7)
	v_mfma_f32_16x16x32_bf16 v[4:7], v[120:123], v[72:75], v[4:7]
	s_waitcnt lgkmcnt(6)
	v_mfma_f32_16x16x32_bf16 v[0:3], v[124:127], v[72:75], v[0:3]
	s_waitcnt vmcnt(14)
	s_waitcnt lgkmcnt(5)
	v_mfma_f32_16x16x32_bf16 v[4:7], v[130:133], v[76:79], v[4:7]
	s_waitcnt lgkmcnt(4)
	v_mfma_f32_16x16x32_bf16 v[0:3], v[134:137], v[76:79], v[0:3]
	s_waitcnt vmcnt(13)
	s_waitcnt lgkmcnt(3)
	v_mfma_f32_16x16x32_bf16 v[4:7], v[138:141], v[80:83], v[4:7]
	s_waitcnt lgkmcnt(2)
	v_mfma_f32_16x16x32_bf16 v[0:3], v[142:145], v[80:83], v[0:3]
	s_waitcnt vmcnt(12)
	s_waitcnt lgkmcnt(1)
	v_mfma_f32_16x16x32_bf16 v[4:7], v[146:149], v[84:87], v[4:7]
	s_waitcnt lgkmcnt(0)
	v_mfma_f32_16x16x32_bf16 v[0:3], v[150:153], v[84:87], v[0:3]
	global_load_dwordx4 v[56:59], v[208:209], off offset:2304
	global_load_dwordx4 v[60:63], v[208:209], off offset:2368
	global_load_dwordx4 v[64:67], v[208:209], off offset:2432
	global_load_dwordx4 v[68:71], v[208:209], off offset:2496
	global_load_dwordx4 v[72:75], v[208:209], off offset:2560
	global_load_dwordx4 v[76:79], v[208:209], off offset:2624
	global_load_dwordx4 v[80:83], v[208:209], off offset:2688
	global_load_dwordx4 v[84:87], v[208:209], off offset:2752
	s_waitcnt vmcnt(8)
	ds_write_b128 v179, v[168:171] offset:0
	ds_write_b128 v179, v[172:175] offset:8704
	v_add_u32_e32 v251, 20, v178
	v_min_u32_e32 v251, 0xfff, v251
	v_or_b32_e32 v251, s6, v251
	v_mul_u32_u24_e32 v128, 0x1830, v251
	v_lshl_add_u64 v[254:255], v[252:253], 0, v[128:129]
	global_load_dwordx4 v[168:171], v[254:255], off
	v_add_u32_e32 v251, 0x114, v178
	v_min_u32_e32 v251, 0xfff, v251
	v_or_b32_e32 v251, s6, v251
	v_mul_u32_u24_e32 v128, 0x1830, v251
	v_lshl_add_u64 v[254:255], v[252:253], 0, v[128:129]
	global_load_dwordx4 v[172:175], v[254:255], off
	s_waitcnt lgkmcnt(0)
	s_barrier
	ds_read_b128 v[88:91], v180 offset:0
	ds_read_b128 v[92:95], v180 offset:8704
	ds_read_b128 v[96:99], v180 offset:64
	ds_read_b128 v[100:103], v180 offset:8768
	ds_read_b128 v[104:107], v180 offset:128
	ds_read_b128 v[108:111], v180 offset:8832
	ds_read_b128 v[112:115], v180 offset:192
	ds_read_b128 v[116:119], v180 offset:8896
	ds_read_b128 v[120:123], v180 offset:256
	ds_read_b128 v[124:127], v180 offset:8960
	ds_read_b128 v[130:133], v180 offset:320
	ds_read_b128 v[134:137], v180 offset:9024
	ds_read_b128 v[138:141], v180 offset:384
	ds_read_b128 v[142:145], v180 offset:9088
	ds_read_b128 v[146:149], v180 offset:448
	ds_read_b128 v[150:153], v180 offset:9152
	s_waitcnt vmcnt(19)
	s_waitcnt lgkmcnt(15)
	v_mfma_f32_16x16x32_bf16 v[4:7], v[88:91], v[24:27], v[4:7]
	s_waitcnt lgkmcnt(14)
	v_mfma_f32_16x16x32_bf16 v[0:3], v[92:95], v[24:27], v[0:3]
	s_waitcnt vmcnt(18)
	s_waitcnt lgkmcnt(13)
	v_mfma_f32_16x16x32_bf16 v[4:7], v[96:99], v[28:31], v[4:7]
	s_waitcnt lgkmcnt(12)
	v_mfma_f32_16x16x32_bf16 v[0:3], v[100:103], v[28:31], v[0:3]
	s_waitcnt vmcnt(17)
	s_waitcnt lgkmcnt(11)
	v_mfma_f32_16x16x32_bf16 v[4:7], v[104:107], v[32:35], v[4:7]
	s_waitcnt lgkmcnt(10)
	v_mfma_f32_16x16x32_bf16 v[0:3], v[108:111], v[32:35], v[0:3]
	s_waitcnt vmcnt(16)
	s_waitcnt lgkmcnt(9)
	v_mfma_f32_16x16x32_bf16 v[4:7], v[112:115], v[36:39], v[4:7]
	s_waitcnt lgkmcnt(8)
	v_mfma_f32_16x16x32_bf16 v[0:3], v[116:119], v[36:39], v[0:3]
	s_waitcnt vmcnt(15)
	s_waitcnt lgkmcnt(7)
	v_mfma_f32_16x16x32_bf16 v[4:7], v[120:123], v[40:43], v[4:7]
	s_waitcnt lgkmcnt(6)
	v_mfma_f32_16x16x32_bf16 v[0:3], v[124:127], v[40:43], v[0:3]
	s_waitcnt vmcnt(14)
	s_waitcnt lgkmcnt(5)
	v_mfma_f32_16x16x32_bf16 v[4:7], v[130:133], v[44:47], v[4:7]
	s_waitcnt lgkmcnt(4)
	v_mfma_f32_16x16x32_bf16 v[0:3], v[134:137], v[44:47], v[0:3]
	s_waitcnt vmcnt(13)
	s_waitcnt lgkmcnt(3)
	v_mfma_f32_16x16x32_bf16 v[4:7], v[138:141], v[48:51], v[4:7]
	s_waitcnt lgkmcnt(2)
	v_mfma_f32_16x16x32_bf16 v[0:3], v[142:145], v[48:51], v[0:3]
	s_waitcnt vmcnt(12)
	s_waitcnt lgkmcnt(1)
	v_mfma_f32_16x16x32_bf16 v[4:7], v[146:149], v[52:55], v[4:7]
	s_waitcnt lgkmcnt(0)
	v_mfma_f32_16x16x32_bf16 v[0:3], v[150:153], v[52:55], v[0:3]
	global_load_dwordx4 v[24:27], v[208:209], off offset:2816
	global_load_dwordx4 v[28:31], v[208:209], off offset:2880
	global_load_dwordx4 v[32:35], v[208:209], off offset:2944
	global_load_dwordx4 v[36:39], v[208:209], off offset:3008
	global_load_dwordx4 v[40:43], v[208:209], off offset:3072
	global_load_dwordx4 v[44:47], v[208:209], off offset:3136
	global_load_dwordx4 v[48:51], v[208:209], off offset:3200
	global_load_dwordx4 v[52:55], v[208:209], off offset:3264
	s_waitcnt vmcnt(8)
	ds_write_b128 v179, v[168:171] offset:17408
	ds_write_b128 v179, v[172:175] offset:26112
	v_add_u32_e32 v251, 24, v178
	v_min_u32_e32 v251, 0xfff, v251
	v_or_b32_e32 v251, s6, v251
	v_mul_u32_u24_e32 v128, 0x1830, v251
	v_lshl_add_u64 v[254:255], v[252:253], 0, v[128:129]
	global_load_dwordx4 v[168:171], v[254:255], off
	v_add_u32_e32 v251, 0x118, v178
	v_min_u32_e32 v251, 0xfff, v251
	v_or_b32_e32 v251, s6, v251
	v_mul_u32_u24_e32 v128, 0x1830, v251
	v_lshl_add_u64 v[254:255], v[252:253], 0, v[128:129]
	global_load_dwordx4 v[172:175], v[254:255], off
	s_waitcnt lgkmcnt(0)
	s_barrier
; #define MFMA16(a, b, c) __builtin_amdgcn_mfma_f32_16x16x32_bf16((a), (b), (c), 0, 0, 0)
; DI void compress_item(const Args& a, int l, int item, LAS unsigned char* lds) {
;     ...
; #pragma unroll 1
;     for (int k8 = 0; k8 < 64; k8 += 8) {
;         bf16x8 bfr[8], af[8][2];
; #pragma unroll
;         for (int kk = 0; kk < 8; ++kk) {
;             const int ks = k8 + kk, tokoff = ks >> 1, dcol = (ks & 1) * 32 + fq * 8;
;             bfr[kk] = *(const bf16x8*)(w1 + ks * 32);
; #pragma unroll
;             for (int m = 0; m < 2; ++m) { int tk = tk0[m] + tokoff; tk = tk > SEQ - 1 ? SEQ - 1 : tk; af[kk][m] = *(const bf16x8*)(PROJ + ((size_t)b * SEQ + tk) * PP + colbase + dcol); }
;         }
; #pragma unroll
;         for (int kk = 0; kk < 8; ++kk)
; #pragma unroll
;             for (int m = 0; m < 2; ++m) acc[m] = MFMA16(af[kk][m], bfr[kk], acc[m]);
;     }
	ds_read_b128 v[88:91], v180 offset:17408
	ds_read_b128 v[92:95], v180 offset:26112
	ds_read_b128 v[96:99], v180 offset:17472
	ds_read_b128 v[100:103], v180 offset:26176
	ds_read_b128 v[104:107], v180 offset:17536
	ds_read_b128 v[108:111], v180 offset:26240
	ds_read_b128 v[112:115], v180 offset:17600
	ds_read_b128 v[116:119], v180 offset:26304
	ds_read_b128 v[120:123], v180 offset:17664
	ds_read_b128 v[124:127], v180 offset:26368
	ds_read_b128 v[130:133], v180 offset:17728
	ds_read_b128 v[134:137], v180 offset:26432
	ds_read_b128 v[138:141], v180 offset:17792
	ds_read_b128 v[142:145], v180 offset:26496
	ds_read_b128 v[146:149], v180 offset:17856
	ds_read_b128 v[150:153], v180 offset:26560
	s_waitcnt vmcnt(19)
	s_waitcnt lgkmcnt(15)
	v_mfma_f32_16x16x32_bf16 v[4:7], v[88:91], v[56:59], v[4:7]
	s_waitcnt lgkmcnt(14)
	v_mfma_f32_16x16x32_bf16 v[0:3], v[92:95], v[56:59], v[0:3]
	s_waitcnt vmcnt(18)
	s_waitcnt lgkmcnt(13)
	v_mfma_f32_16x16x32_bf16 v[4:7], v[96:99], v[60:63], v[4:7]
	s_waitcnt lgkmcnt(12)
	v_mfma_f32_16x16x32_bf16 v[0:3], v[100:103], v[60:63], v[0:3]
	s_waitcnt vmcnt(17)
	s_waitcnt lgkmcnt(11)
	v_mfma_f32_16x16x32_bf16 v[4:7], v[104:107], v[64:67], v[4:7]
	s_waitcnt lgkmcnt(10)
	v_mfma_f32_16x16x32_bf16 v[0:3], v[108:111], v[64:67], v[0:3]
	s_waitcnt vmcnt(16)
	s_waitcnt lgkmcnt(9)
	v_mfma_f32_16x16x32_bf16 v[4:7], v[112:115], v[68:71], v[4:7]
	s_waitcnt lgkmcnt(8)
	v_mfma_f32_16x16x32_bf16 v[0:3], v[116:119], v[68:71], v[0:3]
	s_waitcnt vmcnt(15)
	s_waitcnt lgkmcnt(7)
	v_mfma_f32_16x16x32_bf16 v[4:7], v[120:123], v[72:75], v[4:7]
	s_waitcnt lgkmcnt(6)
	v_mfma_f32_16x16x32_bf16 v[0:3], v[124:127], v[72:75], v[0:3]
	s_waitcnt vmcnt(14)
	s_waitcnt lgkmcnt(5)
	v_mfma_f32_16x16x32_bf16 v[4:7], v[130:133], v[76:79], v[4:7]
	s_waitcnt lgkmcnt(4)
	v_mfma_f32_16x16x32_bf16 v[0:3], v[134:137], v[76:79], v[0:3]
	s_waitcnt vmcnt(13)
	s_waitcnt lgkmcnt(3)
	v_mfma_f32_16x16x32_bf16 v[4:7], v[138:141], v[80:83], v[4:7]
	s_waitcnt lgkmcnt(2)
	v_mfma_f32_16x16x32_bf16 v[0:3], v[142:145], v[80:83], v[0:3]
	s_waitcnt vmcnt(12)
	s_waitcnt lgkmcnt(1)
	v_mfma_f32_16x16x32_bf16 v[4:7], v[146:149], v[84:87], v[4:7]
	s_waitcnt lgkmcnt(0)
	v_mfma_f32_16x16x32_bf16 v[0:3], v[150:153], v[84:87], v[0:3]
	global_load_dwordx4 v[56:59], v[208:209], off offset:3328
	global_load_dwordx4 v[60:63], v[208:209], off offset:3392
	global_load_dwordx4 v[64:67], v[208:209], off offset:3456
	global_load_dwordx4 v[68:71], v[208:209], off offset:3520
	global_load_dwordx4 v[72:75], v[208:209], off offset:3584
	global_load_dwordx4 v[76:79], v[208:209], off offset:3648
	global_load_dwordx4 v[80:83], v[208:209], off offset:3712
	global_load_dwordx4 v[84:87], v[208:209], off offset:3776
	s_waitcnt vmcnt(8)
	ds_write_b128 v179, v[168:171] offset:0
	ds_write_b128 v179, v[172:175] offset:8704
	v_add_u32_e32 v251, 28, v178
	v_min_u32_e32 v251, 0xfff, v251
	v_or_b32_e32 v251, s6, v251
	v_mul_u32_u24_e32 v128, 0x1830, v251
	v_lshl_add_u64 v[254:255], v[252:253], 0, v[128:129]
	global_load_dwordx4 v[168:171], v[254:255], off
	v_add_u32_e32 v251, 0x11c, v178
	v_min_u32_e32 v251, 0xfff, v251
	v_or_b32_e32 v251, s6, v251
	v_mul_u32_u24_e32 v128, 0x1830, v251
	v_lshl_add_u64 v[254:255], v[252:253], 0, v[128:129]
	global_load_dwordx4 v[172:175], v[254:255], off
	s_waitcnt lgkmcnt(0)
	s_barrier
	ds_read_b128 v[88:91], v180 offset:0
	ds_read_b128 v[92:95], v180 offset:8704
	ds_read_b128 v[96:99], v180 offset:64
	ds_read_b128 v[100:103], v180 offset:8768
	ds_read_b128 v[104:107], v180 offset:128
	ds_read_b128 v[108:111], v180 offset:8832
	ds_read_b128 v[112:115], v180 offset:192
	ds_read_b128 v[116:119], v180 offset:8896
	ds_read_b128 v[120:123], v180 offset:256
	ds_read_b128 v[124:127], v180 offset:8960
	ds_read_b128 v[130:133], v180 offset:320
	ds_read_b128 v[134:137], v180 offset:9024
	ds_read_b128 v[138:141], v180 offset:384
	ds_read_b128 v[142:145], v180 offset:9088
	ds_read_b128 v[146:149], v180 offset:448
	ds_read_b128 v[150:153], v180 offset:9152
	s_waitcnt vmcnt(19)
	s_waitcnt lgkmcnt(15)
	v_mfma_f32_16x16x32_bf16 v[4:7], v[88:91], v[24:27], v[4:7]
	s_waitcnt lgkmcnt(14)
	v_mfma_f32_16x16x32_bf16 v[0:3], v[92:95], v[24:27], v[0:3]
	s_waitcnt vmcnt(18)
	s_waitcnt lgkmcnt(13)
	v_mfma_f32_16x16x32_bf16 v[4:7], v[96:99], v[28:31], v[4:7]
	s_waitcnt lgkmcnt(12)
	v_mfma_f32_16x16x32_bf16 v[0:3], v[100:103], v[28:31], v[0:3]
	s_waitcnt vmcnt(17)
	s_waitcnt lgkmcnt(11)
	v_mfma_f32_16x16x32_bf16 v[4:7], v[104:107], v[32:35], v[4:7]
	s_waitcnt lgkmcnt(10)
	v_mfma_f32_16x16x32_bf16 v[0:3], v[108:111], v[32:35], v[0:3]
	s_waitcnt vmcnt(16)
	s_waitcnt lgkmcnt(9)
	v_mfma_f32_16x16x32_bf16 v[4:7], v[112:115], v[36:39], v[4:7]
	s_waitcnt lgkmcnt(8)
	v_mfma_f32_16x16x32_bf16 v[0:3], v[116:119], v[36:39], v[0:3]
	s_waitcnt vmcnt(15)
	s_waitcnt lgkmcnt(7)
	v_mfma_f32_16x16x32_bf16 v[4:7], v[120:123], v[40:43], v[4:7]
	s_waitcnt lgkmcnt(6)
	v_mfma_f32_16x16x32_bf16 v[0:3], v[124:127], v[40:43], v[0:3]
	s_waitcnt vmcnt(14)
	s_waitcnt lgkmcnt(5)
	v_mfma_f32_16x16x32_bf16 v[4:7], v[130:133], v[44:47], v[4:7]
	s_waitcnt lgkmcnt(4)
	v_mfma_f32_16x16x32_bf16 v[0:3], v[134:137], v[44:47], v[0:3]
	s_waitcnt vmcnt(13)
	s_waitcnt lgkmcnt(3)
	v_mfma_f32_16x16x32_bf16 v[4:7], v[138:141], v[48:51], v[4:7]
	s_waitcnt lgkmcnt(2)
	v_mfma_f32_16x16x32_bf16 v[0:3], v[142:145], v[48:51], v[0:3]
	s_waitcnt vmcnt(12)
	s_waitcnt lgkmcnt(1)
	v_mfma_f32_16x16x32_bf16 v[4:7], v[146:149], v[52:55], v[4:7]
	s_waitcnt lgkmcnt(0)
	v_mfma_f32_16x16x32_bf16 v[0:3], v[150:153], v[52:55], v[0:3]
	s_waitcnt vmcnt(0)
	ds_write_b128 v179, v[168:171] offset:17408
	ds_write_b128 v179, v[172:175] offset:26112
	s_waitcnt lgkmcnt(0)
	s_barrier
; #define MFMA16(a, b, c) __builtin_amdgcn_mfma_f32_16x16x32_bf16((a), (b), (c), 0, 0, 0)
; DI void compress_item(const Args& a, int l, int item, LAS unsigned char* lds) {
;     ...
; #pragma unroll
;         for (int kk = 0; kk < 8; ++kk)
; #pragma unroll
;             for (int m = 0; m < 2; ++m) acc[m] = MFMA16(af[kk][m], bfr[kk], acc[m]);
;     }
;     {
;         const int c = wid * 16 + fr; const float* biasp = (const float*)(a.ws + WS_BIASP) + kv * 16 * 128 + c;
;         float bias = 0.f;
; #pragma unroll
;         for (int kp = 0; kp < 16; ++kp) bias += biasp[kp * 128];
	ds_read_b128 v[88:91], v180 offset:17408
	ds_read_b128 v[92:95], v180 offset:26112
	ds_read_b128 v[96:99], v180 offset:17472
	ds_read_b128 v[100:103], v180 offset:26176
	ds_read_b128 v[104:107], v180 offset:17536
	ds_read_b128 v[108:111], v180 offset:26240
	ds_read_b128 v[112:115], v180 offset:17600
	ds_read_b128 v[116:119], v180 offset:26304
	ds_read_b128 v[120:123], v180 offset:17664
	ds_read_b128 v[124:127], v180 offset:26368
	ds_read_b128 v[130:133], v180 offset:17728
	ds_read_b128 v[134:137], v180 offset:26432
	ds_read_b128 v[138:141], v180 offset:17792
	ds_read_b128 v[142:145], v180 offset:26496
	ds_read_b128 v[146:149], v180 offset:17856
	ds_read_b128 v[150:153], v180 offset:26560
	s_waitcnt vmcnt(9)
	s_waitcnt lgkmcnt(15)
	v_mfma_f32_16x16x32_bf16 v[4:7], v[88:91], v[56:59], v[4:7]
	s_waitcnt lgkmcnt(14)
	v_mfma_f32_16x16x32_bf16 v[0:3], v[92:95], v[56:59], v[0:3]
	s_waitcnt vmcnt(8)
	s_waitcnt lgkmcnt(13)
	v_mfma_f32_16x16x32_bf16 v[4:7], v[96:99], v[60:63], v[4:7]
	s_waitcnt lgkmcnt(12)
	v_mfma_f32_16x16x32_bf16 v[0:3], v[100:103], v[60:63], v[0:3]
	s_waitcnt vmcnt(7)
	s_waitcnt lgkmcnt(11)
	v_mfma_f32_16x16x32_bf16 v[4:7], v[104:107], v[64:67], v[4:7]
	s_waitcnt lgkmcnt(10)
	v_mfma_f32_16x16x32_bf16 v[0:3], v[108:111], v[64:67], v[0:3]
	s_waitcnt vmcnt(6)
	s_waitcnt lgkmcnt(9)
	v_mfma_f32_16x16x32_bf16 v[4:7], v[112:115], v[68:71], v[4:7]
	s_waitcnt lgkmcnt(8)
	v_mfma_f32_16x16x32_bf16 v[0:3], v[116:119], v[68:71], v[0:3]
	s_waitcnt vmcnt(5)
	s_waitcnt lgkmcnt(7)
	v_mfma_f32_16x16x32_bf16 v[4:7], v[120:123], v[72:75], v[4:7]
	s_waitcnt lgkmcnt(6)
	v_mfma_f32_16x16x32_bf16 v[0:3], v[124:127], v[72:75], v[0:3]
	s_waitcnt vmcnt(4)
	s_waitcnt lgkmcnt(5)
	v_mfma_f32_16x16x32_bf16 v[4:7], v[130:133], v[76:79], v[4:7]
	s_waitcnt lgkmcnt(4)
	v_mfma_f32_16x16x32_bf16 v[0:3], v[134:137], v[76:79], v[0:3]
	s_waitcnt vmcnt(3)
	s_waitcnt lgkmcnt(3)
	v_mfma_f32_16x16x32_bf16 v[4:7], v[138:141], v[80:83], v[4:7]
	s_waitcnt lgkmcnt(2)
	v_mfma_f32_16x16x32_bf16 v[0:3], v[142:145], v[80:83], v[0:3]
	s_waitcnt vmcnt(2)
	s_waitcnt lgkmcnt(1)
	v_mfma_f32_16x16x32_bf16 v[4:7], v[146:149], v[84:87], v[4:7]
	s_waitcnt lgkmcnt(0)
	v_mfma_f32_16x16x32_bf16 v[0:3], v[150:153], v[84:87], v[0:3]
	s_lshl_b32 s6, s4, 11
	s_ashr_i32 s7, s6, 31
	s_lshl_b64 s[6:7], s[6:7], 2
	v_readlane_b32 s14, v245, 14
	v_readlane_b32 s15, v245, 15
	s_add_u32 s6, s14, s6
	s_addc_u32 s7, s15, s7
	v_lshl_add_u64 v[12:13], v[10:11], 2, s[6:7]
	global_load_dword v11, v[12:13], off
	global_load_dword v24, v[12:13], off offset:512
	global_load_dword v25, v[12:13], off offset:1024
	global_load_dword v26, v[12:13], off offset:1536
	global_load_dword v27, v[12:13], off offset:2048
	global_load_dword v28, v[12:13], off offset:2560
	global_load_dword v29, v[12:13], off offset:3072
	global_load_dword v30, v[12:13], off offset:3584
	s_movk_i32 s6, 0x1000
	v_lshlrev_b32_e32 v10, 1, v10
	s_lshl_b64 s[4:5], s[4:5], 14
	v_bfe_u32 v16, v9, 6, 2
	v_add_co_u32_e32 v12, vcc, s6, v12
	s_movk_i32 s6, 0x110
	s_nop 0
	v_addc_co_u32_e32 v13, vcc, 0, v13, vcc
	global_load_dword v31, v[12:13], off
	global_load_dword v32, v[12:13], off offset:512
	global_load_dword v33, v[12:13], off offset:1024
	global_load_dword v34, v[12:13], off offset:1536
	global_load_dword v35, v[12:13], off offset:2048
	global_load_dword v36, v[12:13], off offset:2560
	global_load_dword v37, v[12:13], off offset:3072
	global_load_dword v38, v[12:13], off offset:3584
	s_waitcnt vmcnt(15)
	v_add_f32_e32 v11, 0, v11
	s_waitcnt vmcnt(14)
	v_add_f32_e32 v11, v11, v24
	s_waitcnt vmcnt(13)
	v_add_f32_e32 v11, v11, v25
	s_waitcnt vmcnt(12)
	v_add_f32_e32 v11, v11, v26
	s_waitcnt vmcnt(11)
	v_add_f32_e32 v11, v11, v27
	s_waitcnt vmcnt(10)
	v_add_f32_e32 v11, v11, v28
	s_waitcnt vmcnt(9)
	v_add_f32_e32 v11, v11, v29
	s_waitcnt vmcnt(8)
	v_add_f32_e32 v11, v11, v30
	s_waitcnt vmcnt(7)
	v_add_f32_e32 v11, v11, v31
	s_waitcnt vmcnt(6)
	v_add_f32_e32 v11, v11, v32
	s_waitcnt vmcnt(5)
	v_add_f32_e32 v11, v11, v33
	s_waitcnt vmcnt(4)
	v_add_f32_e32 v11, v11, v34
	s_waitcnt vmcnt(3)
	v_add_f32_e32 v11, v11, v35
	s_waitcnt vmcnt(2)
	v_add_f32_e32 v11, v11, v36
	s_waitcnt vmcnt(1)
	v_add_f32_e32 v11, v11, v37
	s_waitcnt vmcnt(0)
; #define LAS __attribute__((address_space(3)))
; DI bf16_t tobf(float x) { return (bf16_t)(pk2(x, 0.f) & 0xffffu); }
; DI u32x4 pack8(const float* f) { u32x4 w; w.x = pk2(f[0], f[1]); w.y = pk2(f[2], f[3]); w.z = pk2(f[4], f[5]); w.w = pk2(f[6], f[7]); return w; }
; DI float red8(float x) { x = red4(x); x = dpp_add<0x141>(x); return x; }
; DI void compress_item(const Args& a, int l, int item, LAS unsigned char* lds) {
;     ...
;         const int c = wid * 16 + fr; const float* biasp = (const float*)(a.ws + WS_BIASP) + kv * 16 * 128 + c;
;         float bias = 0.f;
; #pragma unroll
;         for (int kp = 0; kp < 16; ++kp) bias += biasp[kp * 128];
; #pragma unroll
;         for (int m = 0; m < 2; ++m)
; #pragma unroll
;             for (int r = 0; r < 4; ++r) hs[(m * 16 + fq * 4 + r) * 136 + c] = tobf(gelu_tanh(acc[m][r] + bias));
;     }
;     __syncthreads();
;     {
;         const int m = wid >> 2, nt = wid & 3;
;         f32x4 acc2 = {0.f, 0.f, 0.f, 0.f};
; #pragma unroll
;         for (int ks = 0; ks < 4; ++ks) {
;             const bf16x8 af = *(const LAS bf16x8*)(hs + (m * 16 + fr) * 136 + ks * 32 + fq * 8);
;             const bf16x8 bf = *(const bf16x8*)(W + W_C2 + (size_t)kv * 8192 + (size_t)(nt * 16 + fr) * 128 + ks * 32 + fq * 8);
;             acc2 = MFMA16(af, bf, acc2);
;         }
; #pragma unroll
;         for (int r = 0; r < 4; ++r) os[(m * 16 + fq * 4 + r) * 64 + nt * 16 + fr] = acc2[r];
;     }
;     __syncthreads();
;     if (tid < 256) {
;         const int rowi = tid >> 3, d0 = (tid & 7) * 8, n = nq * 32 + rowi;
;         float v[8];
; #pragma unroll
;         for (int i = 0; i < 8; ++i) v[i] = os[rowi * 64 + d0 + i];
;         if (kv == 0) {
;             float ss = 0.f;
; #pragma unroll
;             for (int i = 0; i < 8; ++i) ss += v[i] * v[i];
;             ss = red8(ss);
;             const float rstd = rsqrtf(ss * (1.f / 64.f) + 1e-6f);
;             const float* gn = a.in[I_KGAIN] + (l * 3 + 0) * 64 + d0;
; #pragma unroll
;             for (int i = 0; i < 8; ++i) v[i] = (n == 255) ? 0.f : v[i] * rstd * gn[i];
;             *(u32x4*)((bf16_t*)(a.ws + WS_KCN) + ((size_t)bg * 256 + n) * 64 + d0) = pack8(v);
;         } else {
;             bf16_t* vct = (bf16_t*)(a.ws + WS_VCT) + (size_t)bg * 64 * 256;
; #pragma unroll
;             for (int i = 0; i < 8; ++i) vct[(d0 + i) * 256 + n] = tobf(n == 255 ? 0.f : v[i]);
	v_add_f32_e32 v11, v11, v38
	v_add_f32_e32 v4, v4, v11
	v_mul_f32_e32 v12, 0x3d372713, v4
	v_mul_f32_e32 v12, v4, v12
	v_fma_f32 v12, v4, v12, v4
	v_mul_f32_e32 v12, 0x3f4c422a, v12
	v_add_f32_e32 v12, v12, v12
	v_mul_f32_e32 v12, 0x3fb8aa3b, v12
	v_exp_f32_e32 v12, v12
	v_mul_f32_e32 v4, 0.5, v4
	v_add_f32_e32 v5, v5, v11
	v_add_f32_e32 v0, v0, v11
	v_add_f32_e32 v12, 1.0, v12
	v_rcp_f32_e32 v12, v12
	s_nop 0
	v_fma_f32 v12, v12, -2.0, 1.0
	v_add_f32_e32 v12, 1.0, v12
	v_mul_f32_e32 v4, v4, v12
	v_cvt_pk_bf16_f32 v12, v4, s0
	v_mul_u32_u24_e32 v4, 0x440, v20
	v_add3_u32 v4, 0, v10, v4
	v_mul_f32_e32 v10, 0x3d372713, v5
	v_mul_f32_e32 v10, v5, v10
	v_fma_f32 v10, v5, v10, v5
	v_mul_f32_e32 v10, 0x3f4c422a, v10
	v_add_f32_e32 v10, v10, v10
	v_mul_f32_e32 v10, 0x3fb8aa3b, v10
	v_exp_f32_e32 v10, v10
	v_mul_f32_e32 v5, 0.5, v5
	ds_write_b16 v4, v12
	v_add_f32_e32 v10, 1.0, v10
	v_rcp_f32_e32 v10, v10
	s_nop 0
	v_fma_f32 v10, v10, -2.0, 1.0
	v_add_f32_e32 v10, 1.0, v10
	v_mul_f32_e32 v5, v5, v10
	v_cvt_pk_bf16_f32 v5, v5, s0
	ds_write_b16 v4, v5 offset:272
	v_add_f32_e32 v5, v6, v11
	v_mul_f32_e32 v6, 0x3d372713, v5
	v_mul_f32_e32 v6, v5, v6
	v_fma_f32 v6, v5, v6, v5
	v_mul_f32_e32 v6, 0x3f4c422a, v6
	v_add_f32_e32 v6, v6, v6
	v_mul_f32_e32 v6, 0x3fb8aa3b, v6
	v_exp_f32_e32 v6, v6
	v_mul_f32_e32 v5, 0.5, v5
	v_add_f32_e32 v6, 1.0, v6
	v_rcp_f32_e32 v6, v6
	s_nop 0
	v_fma_f32 v6, v6, -2.0, 1.0
	v_add_f32_e32 v6, 1.0, v6
	v_mul_f32_e32 v5, v5, v6
	v_cvt_pk_bf16_f32 v5, v5, s0
	ds_write_b16 v4, v5 offset:544
	v_add_f32_e32 v5, v7, v11
	v_mul_f32_e32 v6, 0x3d372713, v5
	v_mul_f32_e32 v6, v5, v6
	v_fma_f32 v6, v5, v6, v5
	v_mul_f32_e32 v6, 0x3f4c422a, v6
	v_add_f32_e32 v6, v6, v6
	v_mul_f32_e32 v6, 0x3fb8aa3b, v6
	v_exp_f32_e32 v6, v6
	v_mul_f32_e32 v5, 0.5, v5
	v_add_f32_e32 v6, 1.0, v6
	v_rcp_f32_e32 v6, v6
	s_nop 0
	v_fma_f32 v6, v6, -2.0, 1.0
	v_add_f32_e32 v6, 1.0, v6
	v_mul_f32_e32 v5, v5, v6
	v_cvt_pk_bf16_f32 v5, v5, s0
	ds_write_b16 v4, v5 offset:816
	v_mul_f32_e32 v5, 0x3d372713, v0
	v_mul_f32_e32 v5, v0, v5
	v_fma_f32 v5, v0, v5, v0
	v_mul_f32_e32 v5, 0x3f4c422a, v5
	v_add_f32_e32 v5, v5, v5
	v_mul_f32_e32 v5, 0x3fb8aa3b, v5
	v_exp_f32_e32 v5, v5
	v_mul_f32_e32 v0, 0.5, v0
	v_add_f32_e32 v5, 1.0, v5
	v_rcp_f32_e32 v5, v5
	s_nop 0
	v_fma_f32 v5, v5, -2.0, 1.0
	v_add_f32_e32 v5, 1.0, v5
	v_mul_f32_e32 v0, v0, v5
	v_cvt_pk_bf16_f32 v0, v0, s0
	ds_write_b16 v4, v0 offset:4352
	v_add_f32_e32 v0, v1, v11
	v_mul_f32_e32 v1, 0x3d372713, v0
	v_mul_f32_e32 v1, v0, v1
	v_fma_f32 v1, v0, v1, v0
	v_mul_f32_e32 v1, 0x3f4c422a, v1
	v_add_f32_e32 v1, v1, v1
	v_mul_f32_e32 v1, 0x3fb8aa3b, v1
	v_exp_f32_e32 v1, v1
	v_mul_f32_e32 v0, 0.5, v0
	v_add_f32_e32 v1, 1.0, v1
	v_rcp_f32_e32 v1, v1
	s_nop 0
	v_fma_f32 v1, v1, -2.0, 1.0
	v_add_f32_e32 v1, 1.0, v1
	v_mul_f32_e32 v0, v0, v1
	v_cvt_pk_bf16_f32 v0, v0, s0
	ds_write_b16 v4, v0 offset:4624
	v_add_f32_e32 v0, v2, v11
	v_mul_f32_e32 v1, 0x3d372713, v0
	v_mul_f32_e32 v1, v0, v1
	v_fma_f32 v1, v0, v1, v0
	v_mul_f32_e32 v1, 0x3f4c422a, v1
	v_add_f32_e32 v1, v1, v1
	v_mul_f32_e32 v1, 0x3fb8aa3b, v1
	v_exp_f32_e32 v1, v1
	v_mul_f32_e32 v0, 0.5, v0
	v_add_f32_e32 v1, 1.0, v1
	v_rcp_f32_e32 v1, v1
	s_nop 0
	v_fma_f32 v1, v1, -2.0, 1.0
	v_add_f32_e32 v1, 1.0, v1
	v_mul_f32_e32 v0, v0, v1
	v_cvt_pk_bf16_f32 v0, v0, s0
	ds_write_b16 v4, v0 offset:4896
	v_add_f32_e32 v0, v3, v11
	v_mul_f32_e32 v1, 0x3d372713, v0
	v_mul_f32_e32 v1, v0, v1
	v_fma_f32 v1, v0, v1, v0
	v_mul_f32_e32 v1, 0x3f4c422a, v1
	v_add_f32_e32 v1, v1, v1
	v_mul_f32_e32 v1, 0x3fb8aa3b, v1
	v_exp_f32_e32 v1, v1
	v_mul_f32_e32 v0, 0.5, v0
	v_add_f32_e32 v1, 1.0, v1
	v_rcp_f32_e32 v1, v1
	s_nop 0
	v_fma_f32 v1, v1, -2.0, 1.0
	v_add_f32_e32 v1, 1.0, v1
	v_mul_f32_e32 v0, v0, v1
	v_cvt_pk_bf16_f32 v0, v0, s0
	ds_write_b16 v4, v0 offset:5168
	v_ashrrev_i32_e32 v0, 4, v9
	v_and_b32_e32 v17, -16, v0
	v_or_b32_e32 v0, v17, v21
	v_mul_lo_u32 v1, v0, s6
	v_lshlrev_b32_e32 v0, 1, v8
	v_readlane_b32 s6, v245, 52
	v_add3_u32 v8, 0, v1, v0
	v_readlane_b32 s7, v245, 53
	s_add_u32 s4, s6, s4
	v_lshlrev_b32_e32 v1, 8, v21
	s_addc_u32 s5, s7, s5
	v_lshl_or_b32 v128, v16, 12, v1
	v_lshl_add_u64 v[2:3], s[4:5], 0, v[128:129]
	v_mov_b32_e32 v1, v129
	v_lshl_add_u64 v[14:15], v[2:3], 0, v[0:1]
	s_waitcnt lgkmcnt(0)
	s_barrier
	global_load_dwordx4 v[4:7], v[14:15], off
	global_load_dwordx4 v[10:13], v[14:15], off offset:64
	ds_read_b128 v[0:3], v8
	s_waitcnt vmcnt(1) lgkmcnt(0)
	v_mfma_f32_16x16x32_bf16 v[0:3], v[0:3], v[4:7], 0
	ds_read_b128 v[4:7], v8 offset:64
	s_movk_i32 s4, 0x100
	v_cmp_gt_i32_e32 vcc, s4, v9
	s_waitcnt vmcnt(0) lgkmcnt(0)
	v_mfma_f32_16x16x32_bf16 v[0:3], v[4:7], v[10:13], v[0:3]
	global_load_dwordx4 v[10:13], v[14:15], off offset:128
	ds_read_b128 v[4:7], v8 offset:128
	s_waitcnt vmcnt(0) lgkmcnt(0)
	v_mfma_f32_16x16x32_bf16 v[0:3], v[4:7], v[10:13], v[0:3]
	global_load_dwordx4 v[10:13], v[14:15], off offset:192
	ds_read_b128 v[4:7], v8 offset:192
	s_waitcnt vmcnt(0) lgkmcnt(0)
	v_mfma_f32_16x16x32_bf16 v[0:3], v[4:7], v[10:13], v[0:3]
	v_lshlrev_b32_e32 v4, 6, v16
	v_lshlrev_b32_e32 v5, 2, v21
	v_add3_u32 v4, 0, v4, v5
	v_lshlrev_b32_e32 v5, 10, v20
	v_lshlrev_b32_e32 v6, 8, v17
	v_add3_u32 v4, v4, v5, v6
	s_nop 1
	ds_write2st64_b32 v4, v0, v1 offset0:34 offset1:35
	ds_write2st64_b32 v4, v2, v3 offset0:36 offset1:37
	s_waitcnt lgkmcnt(0)
	s_barrier
	s_and_saveexec_b64 s[4:5], vcc
	s_cbranch_execz .LBB0_598
	v_lshlrev_b32_e32 v0, 3, v9
	v_ashrrev_i32_e32 v8, 3, v9
	v_and_b32_e32 v12, 56, v0
	v_lshlrev_b32_e32 v0, 8, v8
	v_lshlrev_b32_e32 v128, 2, v12
	v_add3_u32 v0, 0, v0, v128
	ds_read_b128 v[4:7], v0 offset:8704
	ds_read_b128 v[0:3], v0 offset:8720
	s_and_b32 s6, s11, 7
	v_lshl_add_u32 v8, s6, 5, v8
	s_mov_b64 s[6:7], -1
	s_and_b64 vcc, exec, s[2:3]
	s_cbranch_vccz .LBB0_608
	s_lshl_b32 s2, s13, 15
	v_readlane_b32 s3, v245, 54
	s_add_u32 s2, s3, s2
	v_readlane_b32 s3, v245, 55
	s_movk_i32 s6, 0xff
	v_lshl_add_u32 v10, v12, 8, v8
	s_addc_u32 s3, s3, 0
	s_waitcnt lgkmcnt(1)
	v_cvt_pk_bf16_f32 v9, v4, s0
	v_cmp_eq_u32_e32 vcc, s6, v8
	v_ashrrev_i32_e32 v11, 31, v10
	v_lshl_add_u64 v[10:11], v[10:11], 1, s[2:3]
	v_cndmask_b32_e64 v9, v9, 0, vcc
	global_store_short v[10:11], v9, off
	v_cvt_pk_bf16_f32 v9, v5, s0
	v_cndmask_b32_e64 v9, v9, 0, vcc
	global_store_short v[10:11], v9, off offset:512
	v_cvt_pk_bf16_f32 v9, v6, s0
	v_cndmask_b32_e64 v9, v9, 0, vcc
	global_store_short v[10:11], v9, off offset:1024
	v_cvt_pk_bf16_f32 v9, v7, s0
	v_cndmask_b32_e64 v9, v9, 0, vcc
	global_store_short v[10:11], v9, off offset:1536
	s_waitcnt lgkmcnt(0)
	v_cvt_pk_bf16_f32 v9, v0, s0
	v_cndmask_b32_e64 v9, v9, 0, vcc
	global_store_short v[10:11], v9, off offset:2048
	v_cvt_pk_bf16_f32 v9, v1, s0
	v_cndmask_b32_e64 v9, v9, 0, vcc
	global_store_short v[10:11], v9, off offset:2560
	v_cvt_pk_bf16_f32 v9, v2, s0
	v_cndmask_b32_e64 v9, v9, 0, vcc
	global_store_short v[10:11], v9, off offset:3072
	v_cvt_pk_bf16_f32 v9, v3, s0
	v_cndmask_b32_e64 v9, v9, 0, vcc
	global_store_short v[10:11], v9, off offset:3584
	s_mov_b64 s[6:7], 0
